# grid barrier: non-leader workgroups wait on the cross-XCD release word directly (no per-XCD release stage); K-loop redundant waits removed
# speedup vs baseline: 1.0264x; 1.0152x over previous
; __device__ __forceinline__ unsigned xb_ld(unsigned* p)              { return __hip_atomic_load(p, __ATOMIC_RELAXED, __HIP_MEMORY_SCOPE_AGENT); }
; __device__ __forceinline__ unsigned xb_add(unsigned* p, unsigned v) { return __hip_atomic_fetch_add(p, v, __ATOMIC_RELAXED, __HIP_MEMORY_SCOPE_AGENT); }
; #define XB_SPIN(cond, bar) do { unsigned _sp = 0; while (cond) { __builtin_amdgcn_s_sleep(1); \
;     if ((++_sp & 255u) == 0u) { if (xb_ld(&(bar)[XB_TMO])) break; if (_sp > XB_SPIN_CAP) { atomicAdd(&(bar)[XB_TMO], 1u); break; } } } } while (0)
; __device__ __forceinline__ void xcd_barrier(const XcdBarrier& b) {
;     asm volatile("s_waitcnt vmcnt(0)" ::: "memory");
;     __syncthreads();
;     if (threadIdx.x == 0) {
;         unsigned* bar = b.bar;
;         __builtin_amdgcn_s_waitcnt(0);
;         unsigned nloc = b.st[0], nx = b.st[1];
;         if (nloc == 0u) { xcd_barrier_complete(bar, b.x, nloc, nx); b.st[0] = nloc; b.st[1] = nx; }
;         const unsigned old = xb_add(&bar[XB_XSUB(b.x)], 1u);
;         const unsigned gen = old / nloc;
;         if (old + 1u == (gen + 1u) * nloc) {
;             __builtin_amdgcn_fence(__ATOMIC_RELEASE, "agent");
;             asm volatile("s_waitcnt vmcnt(0)" ::: "memory");
;             const unsigned og = xb_add(&bar[XB_TOP], 1u);
;             const unsigned tg = og / nx;
;             if (og + 1u == (tg + 1u) * nx) xb_add(&bar[XB_TOPGEN], 1u);
;             else XB_SPIN(xb_ld(&bar[XB_TOPGEN]) == tg, bar);
;             __builtin_amdgcn_fence(__ATOMIC_ACQUIRE, "agent");
;             xb_add(&bar[XB_XGEN(b.x)], 1u);
;             asm volatile("s_waitcnt vmcnt(0)" ::: "memory");
;         } else {
;             XB_SPIN(xb_ld(&bar[XB_XGEN(b.x)]) == gen, bar);
.LBB0_811:
	v_readlane_b32 s0, v254, 6
	s_lshl_b32 s26, s0, 6
	s_lshl_b64 s[2:3], s[26:27], 2
	v_readlane_b32 s8, v254, 11
	v_readlane_b32 s9, v254, 12
	s_add_u32 s8, s8, s2
	s_addc_u32 s9, s9, s3
	v_mov_b32_e32 v1, 0x1000
	v_sub_u32_e32 v4, 0, v2
	s_nop 0
	global_atomic_add v3, v1, v222, s[8:9] offset:1024 sc0
	v_cvt_f32_u32_e32 v1, v2
	v_rcp_iflag_f32_e32 v1, v1
	s_nop 0
	v_mul_f32_e32 v1, 0x4f7ffffe, v1
	v_cvt_u32_f32_e32 v1, v1
	v_mul_lo_u32 v4, v4, v1
	v_mul_hi_u32 v4, v1, v4
	v_add_u32_e32 v1, v1, v4
	s_waitcnt vmcnt(0)
	v_mul_hi_u32 v1, v3, v1
	v_mul_lo_u32 v4, v1, v2
	v_sub_u32_e32 v4, v3, v4
	v_add_u32_e32 v5, 1, v1
	v_cmp_ge_u32_e32 vcc, v4, v2
	v_add_u32_e32 v3, 1, v3
	s_nop 0
	v_cndmask_b32_e32 v1, v1, v5, vcc
	v_sub_u32_e32 v5, v4, v2
	v_cndmask_b32_e32 v4, v4, v5, vcc
	v_add_u32_e32 v5, 1, v1
	v_cmp_ge_u32_e32 vcc, v4, v2
	s_nop 1
	v_cndmask_b32_e32 v1, v1, v5, vcc
	v_mul_lo_u32 v4, v2, v1
	v_add_u32_e32 v2, v4, v2
	v_cmp_ne_u32_e32 vcc, v3, v2
	s_and_saveexec_b64 s[2:3], vcc
	s_xor_b64 s[10:11], exec, s[2:3]
	s_cbranch_execz .LBB0_824
	s_waitcnt lgkmcnt(0)
	v_readlane_b32 s14, v254, 11
	v_readlane_b32 s15, v254, 12
	s_nop 1
	s_add_u32 s14, s14, 0x3500
	s_addc_u32 s15, s15, 0
	global_load_dword v0, v169, s[14:15] sc1
	s_waitcnt vmcnt(0)
	v_cmp_eq_u32_e32 vcc, v0, v1
	s_and_saveexec_b64 s[12:13], vcc
	s_cbranch_execz .LBB0_823
	s_mov_b32 s0, 1
	s_mov_b64 s[20:21], 0
	s_branch .LBB0_815

; __device__ __forceinline__ unsigned xb_ld(unsigned* p)              { return __hip_atomic_load(p, __ATOMIC_RELAXED, __HIP_MEMORY_SCOPE_AGENT); }
; __device__ __forceinline__ unsigned xb_add(unsigned* p, unsigned v) { return __hip_atomic_fetch_add(p, v, __ATOMIC_RELAXED, __HIP_MEMORY_SCOPE_AGENT); }
; #define XB_SPIN(cond, bar) do { unsigned _sp = 0; while (cond) { __builtin_amdgcn_s_sleep(1); \
;     if ((++_sp & 255u) == 0u) { if (xb_ld(&(bar)[XB_TMO])) break; if (_sp > XB_SPIN_CAP) { atomicAdd(&(bar)[XB_TMO], 1u); break; } } } } while (0)
; __device__ __forceinline__ void xcd_barrier(const XcdBarrier& b) {
;     ...
;         const unsigned old = xb_add(&bar[XB_XSUB(b.x)], 1u);
;         const unsigned gen = old / nloc;
;         if (old + 1u == (gen + 1u) * nloc) {
;             __builtin_amdgcn_fence(__ATOMIC_RELEASE, "agent");
;             asm volatile("s_waitcnt vmcnt(0)" ::: "memory");
;             const unsigned og = xb_add(&bar[XB_TOP], 1u);
;             const unsigned tg = og / nx;
;             if (og + 1u == (tg + 1u) * nx) xb_add(&bar[XB_TOPGEN], 1u);
;             else XB_SPIN(xb_ld(&bar[XB_TOPGEN]) == tg, bar);
;             __builtin_amdgcn_fence(__ATOMIC_ACQUIRE, "agent");
;             xb_add(&bar[XB_XGEN(b.x)], 1u);
;             asm volatile("s_waitcnt vmcnt(0)" ::: "memory");
.LBB0_839:
	s_or_b64 exec, exec, s[10:11]
	v_mov_b32_e32 v0, 0x2000
	s_waitcnt vmcnt(0)
	buffer_inv sc1
	s_waitcnt vmcnt(0)
